# prep phase: 64-lane sums via DPP row ops + permlane16/32 swaps instead of 6 ds_bpermute hops (bit-identical); plus GEMM K-loop micro edits
# speedup vs baseline: 1.0071x; 1.0071x over previous
; __device__ __forceinline__ bf16_t f2bf(float x) { return (bf16_t)(cvt_pk_bf16(x, 0.f) & 0xffffu); }
; __device__ __forceinline__ float bf2f(unsigned short x) { return __uint_as_float(((unsigned)x) << 16); }
; __device__ __forceinline__ float wave_sum(float v, int lane) {
; #pragma unroll
;     for (int o = 1; o < 64; o <<= 1) v += __uint_as_float(__builtin_amdgcn_ds_bpermute((lane ^ o) << 2, __float_as_uint(v)));
;     return v;
; __device__ __forceinline__ void prep_phase(const PrepArgs& a, const int wv) {
;     ...
;         size_t kvrow; if (row < RL) kvrow = (size_t)(row >> 12) * SKV + CTXL + (row & 4095); else { const int rc = row - RL; kvrow = (size_t)(rc >> 8) * SKV + (rc & 255); }
;         const float cA = cur.cA, sA = cur.sA, cB = cur.cB, sB = cur.sB;
; #pragma unroll
;         for (int h = 0; h < 8; ++h) { const float x1 = bf2f((unsigned short)cur.q1[h]), x2 = bf2f((unsigned short)cur.q2[h]);
;             const float rinv = rsqrtf(wave_sum(x1 * x1 + x2 * x2, lane) * (1.f / 128.f) + EPS); const float y1 = x1 * rinv * gq1, y2 = x2 * rinv * gq2;
;             bf16_t* q = a.QA + (size_t)row * 1024 + h * 128; q[lane] = f2bf(y1 * cA - y2 * sA); q[64 + lane] = f2bf(y1 * sA + y2 * cA); }
; #pragma unroll
;         for (int h = 0; h < 2; ++h) { const float x1 = bf2f((unsigned short)cur.k1[h]), x2 = bf2f((unsigned short)cur.k2[h]);
;             const float rinv = rsqrtf(wave_sum(x1 * x1 + x2 * x2, lane) * (1.f / 128.f) + EPS); const float y1 = x1 * rinv * gk1, y2 = x2 * rinv * gk2;
;             bf16_t* k = a.KA + kvrow * 256 + h * 128; k[lane] = f2bf(y1 * cA - y2 * sA); k[64 + lane] = f2bf(y1 * sA + y2 * cA); }
.LBB0_684:
	s_or_b64 exec, exec, s[44:45]
	s_movk_i32 s2, 0x3fff
	v_cmp_lt_i32_e32 vcc, s2, v122
	s_and_saveexec_b64 s[4:5], vcc
	s_xor_b64 s[44:45], exec, s[4:5]
	v_add_u32_e32 v74, 0xffffc000, v122
	v_lshrrev_b32_e32 v74, 8, v74
	v_mul_hi_u32_u24_e32 v75, 0x1100, v74
	v_mul_u32_u24_e32 v74, 0x1100, v74
	s_movk_i32 s2, 0xff
	v_and_or_b32 v74, v122, s2, v74
	s_andn2_saveexec_b64 s[44:45], s[44:45]
	v_ashrrev_i32_e32 v74, 12, v122
	v_and_b32_e32 v122, 0xfff, v122
	v_mul_hi_i32_i24_e32 v75, 0x1100, v74
	v_mul_i32_i24_e32 v74, 0x1100, v74
	v_add_u32_e32 v192, 0x100, v122
	v_lshl_add_u64 v[74:75], v[74:75], 0, v[192:193]
	s_or_b64 exec, exec, s[44:45]
	v_lshlrev_b32_e32 v87, 16, v87
	v_lshlrev_b32_e32 v86, 16, v86
	v_pk_mul_f32 v[122:123], v[86:87], v[86:87]
	s_mov_b32 s2, 0x19e6f000
	v_add_f32_e32 v122, v122, v123
	v_lshlrev_b32_e32 v95, 16, v95
	v_lshlrev_b32_e32 v94, 16, v94
	v_lshlrev_b32_e32 v93, 16, v93
	v_lshlrev_b32_e32 v92, 16, v92
	s_waitcnt lgkmcnt(0)
	s_nop 1
	v_add_f32_dpp v122, v122, v122 quad_perm:[1,0,3,2] row_mask:0xf bank_mask:0xf bound_ctrl:1
	v_lshlrev_b32_e32 v91, 16, v91
	v_lshlrev_b32_e32 v90, 16, v90
	v_lshlrev_b32_e32 v89, 16, v89
	v_lshlrev_b32_e32 v88, 16, v88
	s_waitcnt lgkmcnt(0)
	s_nop 1
	v_add_f32_dpp v122, v122, v122 quad_perm:[2,3,0,1] row_mask:0xf bank_mask:0xf bound_ctrl:1
	v_lshlrev_b32_e32 v85, 16, v85
	v_lshlrev_b32_e32 v84, 16, v84
	v_lshlrev_b32_e32 v83, 16, v83
	v_lshlrev_b32_e32 v82, 16, v82
	s_waitcnt lgkmcnt(0)
	s_nop 1
	v_add_f32_dpp v122, v122, v122 row_half_mirror row_mask:0xf bank_mask:0xf bound_ctrl:1
	v_lshlrev_b32_e32 v81, 16, v81
	v_lshlrev_b32_e32 v80, 16, v80
	v_lshlrev_b32_e32 v79, 16, v79
	v_lshlrev_b32_e32 v78, 16, v78
	s_waitcnt lgkmcnt(0)
	s_nop 1
	v_add_f32_dpp v122, v122, v122 row_mirror row_mask:0xf bank_mask:0xf bound_ctrl:1
	v_mov_b32_e32 v123, v122
	v_lshlrev_b32_e32 v77, 16, v77
	v_lshlrev_b32_e32 v76, 16, v76
	s_waitcnt lgkmcnt(0)
	s_nop 1
	v_permlane16_swap_b32_e32 v122, v123
	v_add_f32_e32 v122, v122, v123
	v_mov_b32_e32 v123, v122
	s_waitcnt lgkmcnt(0)
	s_nop 1
	v_permlane32_swap_b32_e32 v122, v123
	v_add_f32_e32 v122, v122, v123
	v_fmamk_f32 v122, v122, 0x3c000000, v241
	v_cmp_gt_f32_e32 vcc, s68, v122
	v_mul_f32_e32 v123, 0x4b800000, v122
	s_nop 0
	v_cndmask_b32_e32 v122, v122, v123, vcc
	v_rsq_f32_e32 v122, v122
	s_nop 0
	v_mul_f32_e32 v123, 0x45800000, v122
	v_cndmask_b32_e32 v122, v122, v123, vcc
	v_mul_f32_e32 v86, v122, v86
	v_mul_f32_e32 v123, v98, v86
	v_mul_f32_e32 v86, v122, v87
	v_mul_f32_e32 v122, v99, v86
	v_mul_f32_e32 v86, v121, v122
	v_fma_f32 v86, v120, v123, -v86
	v_cvt_pk_bf16_f32 v124, v86, v193
	v_lshl_add_u64 v[86:87], s[16:17], 0, v[36:37]
	v_add_co_u32_e32 v86, vcc, s2, v86
	v_mul_f32_e32 v122, v120, v122
	s_nop 0
	v_addc_co_u32_e32 v87, vcc, 0, v87, vcc
	v_fmac_f32_e32 v122, v121, v123
	global_store_short v[86:87], v124, off
	v_cvt_pk_bf16_f32 v122, v122, v193
	global_store_short v[86:87], v122, off offset:128
	v_pk_mul_f32 v[122:123], v[94:95], v[94:95]
	s_nop 0
	v_add_f32_e32 v122, v122, v123
	s_waitcnt lgkmcnt(0)
	s_nop 1
	v_add_f32_dpp v122, v122, v122 quad_perm:[1,0,3,2] row_mask:0xf bank_mask:0xf bound_ctrl:1
	s_waitcnt lgkmcnt(0)
	s_nop 1
	v_add_f32_dpp v122, v122, v122 quad_perm:[2,3,0,1] row_mask:0xf bank_mask:0xf bound_ctrl:1
	s_waitcnt lgkmcnt(0)
	s_nop 1
	v_add_f32_dpp v122, v122, v122 row_half_mirror row_mask:0xf bank_mask:0xf bound_ctrl:1
	s_waitcnt lgkmcnt(0)
	s_nop 1
	v_add_f32_dpp v122, v122, v122 row_mirror row_mask:0xf bank_mask:0xf bound_ctrl:1
	v_mov_b32_e32 v123, v122
	s_waitcnt lgkmcnt(0)
	s_nop 1
	v_permlane16_swap_b32_e32 v122, v123
	v_add_f32_e32 v122, v122, v123
	v_mov_b32_e32 v123, v122
	s_waitcnt lgkmcnt(0)
	s_nop 1
	v_permlane32_swap_b32_e32 v122, v123
	v_add_f32_e32 v122, v122, v123
	v_fmamk_f32 v122, v122, 0x3c000000, v241
	v_cmp_gt_f32_e32 vcc, s68, v122
	v_mul_f32_e32 v123, 0x4b800000, v122
	s_nop 0
	v_cndmask_b32_e32 v122, v122, v123, vcc
	v_rsq_f32_e32 v122, v122
	s_nop 0
	v_mul_f32_e32 v123, 0x45800000, v122
	v_cndmask_b32_e32 v122, v122, v123, vcc
	v_mul_f32_e32 v95, v122, v95
	v_mul_f32_e32 v94, v122, v94
	v_mul_f32_e32 v95, v99, v95
	v_mul_f32_e32 v94, v98, v94
	v_mul_f32_e32 v122, v121, v95
	v_fma_f32 v122, v120, v94, -v122
	v_mul_f32_e32 v95, v120, v95
	v_cvt_pk_bf16_f32 v122, v122, v193
	global_store_short v[86:87], v122, off offset:256
	v_fmac_f32_e32 v95, v121, v94
	v_cvt_pk_bf16_f32 v94, v95, v193
	global_store_short v[86:87], v94, off offset:384
	v_pk_mul_f32 v[94:95], v[92:93], v[92:93]
	s_nop 0
	v_add_f32_e32 v94, v94, v95
	s_waitcnt lgkmcnt(0)
	s_nop 1
	v_add_f32_dpp v94, v94, v94 quad_perm:[1,0,3,2] row_mask:0xf bank_mask:0xf bound_ctrl:1
	s_waitcnt lgkmcnt(0)
	s_nop 1
	v_add_f32_dpp v94, v94, v94 quad_perm:[2,3,0,1] row_mask:0xf bank_mask:0xf bound_ctrl:1
	s_waitcnt lgkmcnt(0)
	s_nop 1
	v_add_f32_dpp v94, v94, v94 row_half_mirror row_mask:0xf bank_mask:0xf bound_ctrl:1
	s_waitcnt lgkmcnt(0)
	s_nop 1
	v_add_f32_dpp v94, v94, v94 row_mirror row_mask:0xf bank_mask:0xf bound_ctrl:1
	v_mov_b32_e32 v95, v94
	s_waitcnt lgkmcnt(0)
	s_nop 1
	v_permlane16_swap_b32_e32 v94, v95
	v_add_f32_e32 v94, v94, v95
	v_mov_b32_e32 v95, v94
	s_waitcnt lgkmcnt(0)
	s_nop 1
	v_permlane32_swap_b32_e32 v94, v95
	v_add_f32_e32 v94, v94, v95
	v_fmamk_f32 v94, v94, 0x3c000000, v241
	v_cmp_gt_f32_e32 vcc, s68, v94
	v_mul_f32_e32 v95, 0x4b800000, v94
	s_nop 0
	v_cndmask_b32_e32 v94, v94, v95, vcc
	v_rsq_f32_e32 v94, v94
	s_nop 0
	v_mul_f32_e32 v95, 0x45800000, v94
	v_cndmask_b32_e32 v94, v94, v95, vcc
	v_mul_f32_e32 v93, v94, v93
	v_mul_f32_e32 v92, v94, v92
	v_mul_f32_e32 v93, v99, v93
	v_mul_f32_e32 v92, v98, v92
	v_mul_f32_e32 v94, v121, v93
	v_fma_f32 v94, v120, v92, -v94
	v_mul_f32_e32 v93, v120, v93
	v_cvt_pk_bf16_f32 v94, v94, v193
	global_store_short v[86:87], v94, off offset:512
	v_fmac_f32_e32 v93, v121, v92
	v_cvt_pk_bf16_f32 v92, v93, v193
	global_store_short v[86:87], v92, off offset:640
	v_pk_mul_f32 v[92:93], v[90:91], v[90:91]
	s_nop 0
	v_add_f32_e32 v92, v92, v93
	s_waitcnt lgkmcnt(0)
; __device__ __forceinline__ bf16_t f2bf(float x) { return (bf16_t)(cvt_pk_bf16(x, 0.f) & 0xffffu); }
; __device__ __forceinline__ float bf2f(unsigned short x) { return __uint_as_float(((unsigned)x) << 16); }
; __device__ __forceinline__ float wave_sum(float v, int lane) {
; #pragma unroll
;     for (int o = 1; o < 64; o <<= 1) v += __uint_as_float(__builtin_amdgcn_ds_bpermute((lane ^ o) << 2, __float_as_uint(v)));
;     return v;
; __device__ __forceinline__ void prep_phase(const PrepArgs& a, const int wv) {
;     ...
;         for (int h = 0; h < 8; ++h) { const float x1 = bf2f((unsigned short)cur.q1[h]), x2 = bf2f((unsigned short)cur.q2[h]);
;             const float rinv = rsqrtf(wave_sum(x1 * x1 + x2 * x2, lane) * (1.f / 128.f) + EPS); const float y1 = x1 * rinv * gq1, y2 = x2 * rinv * gq2;
;             bf16_t* q = a.QA + (size_t)row * 1024 + h * 128; q[lane] = f2bf(y1 * cA - y2 * sA); q[64 + lane] = f2bf(y1 * sA + y2 * cA); }
	s_nop 1
	v_add_f32_dpp v92, v92, v92 quad_perm:[1,0,3,2] row_mask:0xf bank_mask:0xf bound_ctrl:1
	s_waitcnt lgkmcnt(0)
	s_nop 1
	v_add_f32_dpp v92, v92, v92 quad_perm:[2,3,0,1] row_mask:0xf bank_mask:0xf bound_ctrl:1
	s_waitcnt lgkmcnt(0)
	s_nop 1
	v_add_f32_dpp v92, v92, v92 row_half_mirror row_mask:0xf bank_mask:0xf bound_ctrl:1
	s_waitcnt lgkmcnt(0)
	s_nop 1
	v_add_f32_dpp v92, v92, v92 row_mirror row_mask:0xf bank_mask:0xf bound_ctrl:1
	v_mov_b32_e32 v93, v92
	s_waitcnt lgkmcnt(0)
	s_nop 1
	v_permlane16_swap_b32_e32 v92, v93
	v_add_f32_e32 v92, v92, v93
	v_mov_b32_e32 v93, v92
	s_waitcnt lgkmcnt(0)
	s_nop 1
	v_permlane32_swap_b32_e32 v92, v93
	v_add_f32_e32 v92, v92, v93
	v_fmamk_f32 v92, v92, 0x3c000000, v241
	v_cmp_gt_f32_e32 vcc, s68, v92
	v_mul_f32_e32 v93, 0x4b800000, v92
	s_nop 0
	v_cndmask_b32_e32 v92, v92, v93, vcc
	v_rsq_f32_e32 v92, v92
	s_nop 0
	v_mul_f32_e32 v93, 0x45800000, v92
	v_cndmask_b32_e32 v92, v92, v93, vcc
	v_mul_f32_e32 v91, v92, v91
	v_mul_f32_e32 v90, v92, v90
	v_mul_f32_e32 v91, v99, v91
	v_mul_f32_e32 v90, v98, v90
	v_mul_f32_e32 v92, v121, v91
	v_fma_f32 v92, v120, v90, -v92
	v_mul_f32_e32 v91, v120, v91
	v_cvt_pk_bf16_f32 v92, v92, v193
	global_store_short v[86:87], v92, off offset:768
	v_fmac_f32_e32 v91, v121, v90
	v_cvt_pk_bf16_f32 v90, v91, v193
	global_store_short v[86:87], v90, off offset:896
	v_pk_mul_f32 v[90:91], v[88:89], v[88:89]
	s_nop 0
	v_add_f32_e32 v90, v90, v91
	s_waitcnt lgkmcnt(0)
	s_nop 1
	v_add_f32_dpp v90, v90, v90 quad_perm:[1,0,3,2] row_mask:0xf bank_mask:0xf bound_ctrl:1
	s_waitcnt lgkmcnt(0)
	s_nop 1
	v_add_f32_dpp v90, v90, v90 quad_perm:[2,3,0,1] row_mask:0xf bank_mask:0xf bound_ctrl:1
	s_waitcnt lgkmcnt(0)
	s_nop 1
	v_add_f32_dpp v90, v90, v90 row_half_mirror row_mask:0xf bank_mask:0xf bound_ctrl:1
	s_waitcnt lgkmcnt(0)
	s_nop 1
	v_add_f32_dpp v90, v90, v90 row_mirror row_mask:0xf bank_mask:0xf bound_ctrl:1
	v_mov_b32_e32 v91, v90
	s_waitcnt lgkmcnt(0)
	s_nop 1
	v_permlane16_swap_b32_e32 v90, v91
	v_add_f32_e32 v90, v90, v91
	v_mov_b32_e32 v91, v90
	s_waitcnt lgkmcnt(0)
	s_nop 1
	v_permlane32_swap_b32_e32 v90, v91
	v_add_f32_e32 v90, v90, v91
	v_fmamk_f32 v90, v90, 0x3c000000, v241
	v_cmp_gt_f32_e32 vcc, s68, v90
	v_mul_f32_e32 v91, 0x4b800000, v90
	s_nop 0
	v_cndmask_b32_e32 v90, v90, v91, vcc
	v_rsq_f32_e32 v90, v90
	s_nop 0
	v_mul_f32_e32 v91, 0x45800000, v90
	v_cndmask_b32_e32 v90, v90, v91, vcc
	v_mul_f32_e32 v89, v90, v89
	v_mul_f32_e32 v88, v90, v88
	v_mul_f32_e32 v89, v99, v89
	v_mul_f32_e32 v88, v98, v88
	v_mul_f32_e32 v90, v121, v89
	v_fma_f32 v90, v120, v88, -v90
	v_mul_f32_e32 v89, v120, v89
	v_cvt_pk_bf16_f32 v90, v90, v193
	global_store_short v[86:87], v90, off offset:1024
	v_fmac_f32_e32 v89, v121, v88
	v_cvt_pk_bf16_f32 v88, v89, v193
	global_store_short v[86:87], v88, off offset:1152
	v_pk_mul_f32 v[88:89], v[84:85], v[84:85]
	s_nop 0
	v_add_f32_e32 v88, v88, v89
	s_waitcnt lgkmcnt(0)
	s_nop 1
	v_add_f32_dpp v88, v88, v88 quad_perm:[1,0,3,2] row_mask:0xf bank_mask:0xf bound_ctrl:1
	s_waitcnt lgkmcnt(0)
	s_nop 1
	v_add_f32_dpp v88, v88, v88 quad_perm:[2,3,0,1] row_mask:0xf bank_mask:0xf bound_ctrl:1
	s_waitcnt lgkmcnt(0)
	s_nop 1
	v_add_f32_dpp v88, v88, v88 row_half_mirror row_mask:0xf bank_mask:0xf bound_ctrl:1
	s_waitcnt lgkmcnt(0)
	s_nop 1
	v_add_f32_dpp v88, v88, v88 row_mirror row_mask:0xf bank_mask:0xf bound_ctrl:1
	v_mov_b32_e32 v89, v88
	s_waitcnt lgkmcnt(0)
	s_nop 1
	v_permlane16_swap_b32_e32 v88, v89
	v_add_f32_e32 v88, v88, v89
	v_mov_b32_e32 v89, v88
	s_waitcnt lgkmcnt(0)
	s_nop 1
	v_permlane32_swap_b32_e32 v88, v89
	v_add_f32_e32 v88, v88, v89
	v_fmamk_f32 v88, v88, 0x3c000000, v241
	v_cmp_gt_f32_e32 vcc, s68, v88
	v_mul_f32_e32 v89, 0x4b800000, v88
	s_nop 0
	v_cndmask_b32_e32 v88, v88, v89, vcc
	v_rsq_f32_e32 v88, v88
	s_nop 0
	v_mul_f32_e32 v89, 0x45800000, v88
	v_cndmask_b32_e32 v88, v88, v89, vcc
	v_mul_f32_e32 v85, v88, v85
	v_mul_f32_e32 v84, v88, v84
	v_mul_f32_e32 v85, v99, v85
	v_mul_f32_e32 v84, v98, v84
	v_mul_f32_e32 v88, v121, v85
	v_fma_f32 v88, v120, v84, -v88
	v_mul_f32_e32 v85, v120, v85
	v_cvt_pk_bf16_f32 v88, v88, v193
	global_store_short v[86:87], v88, off offset:1280
	v_fmac_f32_e32 v85, v121, v84
	v_cvt_pk_bf16_f32 v84, v85, v193
	global_store_short v[86:87], v84, off offset:1408
	v_pk_mul_f32 v[84:85], v[82:83], v[82:83]
	s_nop 0
	v_add_f32_e32 v84, v84, v85
	s_waitcnt lgkmcnt(0)
	s_nop 1
	v_add_f32_dpp v84, v84, v84 quad_perm:[1,0,3,2] row_mask:0xf bank_mask:0xf bound_ctrl:1
	s_waitcnt lgkmcnt(0)
	s_nop 1
	v_add_f32_dpp v84, v84, v84 quad_perm:[2,3,0,1] row_mask:0xf bank_mask:0xf bound_ctrl:1
	s_waitcnt lgkmcnt(0)
	s_nop 1
	v_add_f32_dpp v84, v84, v84 row_half_mirror row_mask:0xf bank_mask:0xf bound_ctrl:1
	s_waitcnt lgkmcnt(0)
	s_nop 1
	v_add_f32_dpp v84, v84, v84 row_mirror row_mask:0xf bank_mask:0xf bound_ctrl:1
	v_mov_b32_e32 v85, v84
	s_waitcnt lgkmcnt(0)
	s_nop 1
	v_permlane16_swap_b32_e32 v84, v85
	v_add_f32_e32 v84, v84, v85
	v_mov_b32_e32 v85, v84
	s_waitcnt lgkmcnt(0)
	s_nop 1
	v_permlane32_swap_b32_e32 v84, v85
	v_add_f32_e32 v84, v84, v85
	v_fmamk_f32 v84, v84, 0x3c000000, v241
	v_cmp_gt_f32_e32 vcc, s68, v84
	v_mul_f32_e32 v85, 0x4b800000, v84
	s_nop 0
	v_cndmask_b32_e32 v84, v84, v85, vcc
	v_rsq_f32_e32 v84, v84
	s_nop 0
	v_mul_f32_e32 v85, 0x45800000, v84
	v_cndmask_b32_e32 v84, v84, v85, vcc
	v_mul_f32_e32 v83, v84, v83
	v_mul_f32_e32 v82, v84, v82
	v_mul_f32_e32 v83, v99, v83
	v_mul_f32_e32 v82, v98, v82
	v_mul_f32_e32 v84, v121, v83
	v_fma_f32 v84, v120, v82, -v84
	v_mul_f32_e32 v83, v120, v83
	v_cvt_pk_bf16_f32 v84, v84, v193
	global_store_short v[86:87], v84, off offset:1536
	v_fmac_f32_e32 v83, v121, v82
	v_cvt_pk_bf16_f32 v82, v83, v193
	global_store_short v[86:87], v82, off offset:1664
	v_pk_mul_f32 v[82:83], v[80:81], v[80:81]
	s_nop 0
	v_add_f32_e32 v82, v82, v83
	s_waitcnt lgkmcnt(0)
; __device__ __forceinline__ bf16_t f2bf(float x) { return (bf16_t)(cvt_pk_bf16(x, 0.f) & 0xffffu); }
; __device__ __forceinline__ float bf2f(unsigned short x) { return __uint_as_float(((unsigned)x) << 16); }
; __device__ __forceinline__ void prep_phase(const PrepArgs& a, const int wv) {
;     ...
;         for (int h = 0; h < 8; ++h) { const float x1 = bf2f((unsigned short)cur.q1[h]), x2 = bf2f((unsigned short)cur.q2[h]);
;             const float rinv = rsqrtf(wave_sum(x1 * x1 + x2 * x2, lane) * (1.f / 128.f) + EPS); const float y1 = x1 * rinv * gq1, y2 = x2 * rinv * gq2;
;             bf16_t* q = a.QA + (size_t)row * 1024 + h * 128; q[lane] = f2bf(y1 * cA - y2 * sA); q[64 + lane] = f2bf(y1 * sA + y2 * cA); }
; #pragma unroll
;         for (int h = 0; h < 2; ++h) { const float x1 = bf2f((unsigned short)cur.k1[h]), x2 = bf2f((unsigned short)cur.k2[h]);
;             const float rinv = rsqrtf(wave_sum(x1 * x1 + x2 * x2, lane) * (1.f / 128.f) + EPS); const float y1 = x1 * rinv * gk1, y2 = x2 * rinv * gk2;
;             bf16_t* k = a.KA + kvrow * 256 + h * 128; k[lane] = f2bf(y1 * cA - y2 * sA); k[64 + lane] = f2bf(y1 * sA + y2 * cA); }
;         *(u32x2*)(a.VA + kvrow * 256 + lane * 4) = cur.av;
;         { const bf16x8 q8 = cur.bq;
;           const f32x4 v0 = {bf2f((unsigned short)q8[0]), bf2f((unsigned short)q8[1]), bf2f((unsigned short)q8[2]), bf2f((unsigned short)q8[3])}, v1 = {bf2f((unsigned short)q8[4]), bf2f((unsigned short)q8[5]), bf2f((unsigned short)q8[6]), bf2f((unsigned short)q8[7])};
;           const float ss = (v0[0] * v0[0] + v0[1] * v0[1]) + (v0[2] * v0[2] + v0[3] * v0[3]) + (v1[0] * v1[0] + v1[1] * v1[1]) + (v1[2] * v1[2] + v1[3] * v1[3]);
;           const float rinv = rsqrtf(wave_sum(ss, lane) * (1.f / 512.f) + EPS); const f32x4 o0 = v0 * rinv * gb0, o1 = v1 * rinv * gb1;
	s_nop 1
	v_add_f32_dpp v82, v82, v82 quad_perm:[1,0,3,2] row_mask:0xf bank_mask:0xf bound_ctrl:1
	s_waitcnt lgkmcnt(0)
	s_nop 1
	v_add_f32_dpp v82, v82, v82 quad_perm:[2,3,0,1] row_mask:0xf bank_mask:0xf bound_ctrl:1
	s_waitcnt lgkmcnt(0)
	s_nop 1
	v_add_f32_dpp v82, v82, v82 row_half_mirror row_mask:0xf bank_mask:0xf bound_ctrl:1
	s_waitcnt lgkmcnt(0)
	s_nop 1
	v_add_f32_dpp v82, v82, v82 row_mirror row_mask:0xf bank_mask:0xf bound_ctrl:1
	v_mov_b32_e32 v83, v82
	s_waitcnt lgkmcnt(0)
	s_nop 1
	v_permlane16_swap_b32_e32 v82, v83
	v_add_f32_e32 v82, v82, v83
	v_mov_b32_e32 v83, v82
	s_waitcnt lgkmcnt(0)
	s_nop 1
	v_permlane32_swap_b32_e32 v82, v83
	v_add_f32_e32 v82, v82, v83
	v_fmamk_f32 v82, v82, 0x3c000000, v241
	v_cmp_gt_f32_e32 vcc, s68, v82
	v_mul_f32_e32 v83, 0x4b800000, v82
	s_nop 0
	v_cndmask_b32_e32 v82, v82, v83, vcc
	v_rsq_f32_e32 v82, v82
	s_nop 0
	v_mul_f32_e32 v83, 0x45800000, v82
	v_cndmask_b32_e32 v82, v82, v83, vcc
	v_mul_f32_e32 v81, v82, v81
	v_mul_f32_e32 v80, v82, v80
	v_mul_f32_e32 v81, v99, v81
	v_mul_f32_e32 v80, v98, v80
	v_mul_f32_e32 v82, v121, v81
	v_fma_f32 v82, v120, v80, -v82
	v_cvt_pk_bf16_f32 v82, v82, v193
	global_store_short v[86:87], v82, off offset:1792
	v_pk_mul_f32 v[82:83], v[78:79], v[78:79]
	v_mul_f32_e32 v81, v120, v81
	v_add_f32_e32 v82, v82, v83
	v_fmac_f32_e32 v81, v121, v80
	v_cvt_pk_bf16_f32 v80, v81, v193
	global_store_short v[86:87], v80, off offset:1920
	v_lshlrev_b64 v[80:81], 9, v[74:75]
	s_waitcnt lgkmcnt(0)
	s_nop 1
	v_add_f32_dpp v82, v82, v82 quad_perm:[1,0,3,2] row_mask:0xf bank_mask:0xf bound_ctrl:1
	s_waitcnt lgkmcnt(0)
	s_nop 1
	v_add_f32_dpp v82, v82, v82 quad_perm:[2,3,0,1] row_mask:0xf bank_mask:0xf bound_ctrl:1
	s_waitcnt lgkmcnt(0)
	s_nop 1
	v_add_f32_dpp v82, v82, v82 row_half_mirror row_mask:0xf bank_mask:0xf bound_ctrl:1
	s_waitcnt lgkmcnt(0)
	s_nop 1
	v_add_f32_dpp v82, v82, v82 row_mirror row_mask:0xf bank_mask:0xf bound_ctrl:1
	v_mov_b32_e32 v83, v82
	s_waitcnt lgkmcnt(0)
	s_nop 1
	v_permlane16_swap_b32_e32 v82, v83
	v_add_f32_e32 v82, v82, v83
	v_mov_b32_e32 v83, v82
	s_waitcnt lgkmcnt(0)
	s_nop 1
	v_permlane32_swap_b32_e32 v82, v83
	v_add_f32_e32 v82, v82, v83
	v_fmamk_f32 v82, v82, 0x3c000000, v241
	v_cmp_gt_f32_e32 vcc, s68, v82
	v_mul_f32_e32 v83, 0x4b800000, v82
	s_nop 0
	v_cndmask_b32_e32 v82, v82, v83, vcc
	v_rsq_f32_e32 v82, v82
	s_nop 0
	v_mul_f32_e32 v83, 0x45800000, v82
	v_cndmask_b32_e32 v82, v82, v83, vcc
	v_mul_f32_e32 v78, v82, v78
	v_mul_f32_e32 v83, v100, v78
	v_mul_f32_e32 v78, v82, v79
	v_mul_f32_e32 v82, v101, v78
	v_mul_f32_e32 v78, v121, v82
	v_fma_f32 v78, v120, v83, -v78
	v_mul_f32_e32 v82, v120, v82
	v_cvt_pk_bf16_f32 v84, v78, v193
	v_lshl_add_u64 v[78:79], v[24:25], 0, v[80:81]
	v_fmac_f32_e32 v82, v121, v83
	global_store_short v[78:79], v84, off
	v_cvt_pk_bf16_f32 v82, v82, v193
	global_store_short v[78:79], v82, off offset:128
	v_pk_mul_f32 v[82:83], v[76:77], v[76:77]
	s_nop 0
	v_add_f32_e32 v82, v82, v83
	s_waitcnt lgkmcnt(0)
	s_nop 1
	v_add_f32_dpp v82, v82, v82 quad_perm:[1,0,3,2] row_mask:0xf bank_mask:0xf bound_ctrl:1
	s_waitcnt lgkmcnt(0)
	s_nop 1
	v_add_f32_dpp v82, v82, v82 quad_perm:[2,3,0,1] row_mask:0xf bank_mask:0xf bound_ctrl:1
	s_waitcnt lgkmcnt(0)
	s_nop 1
	v_add_f32_dpp v82, v82, v82 row_half_mirror row_mask:0xf bank_mask:0xf bound_ctrl:1
	s_waitcnt lgkmcnt(0)
	s_nop 1
	v_add_f32_dpp v82, v82, v82 row_mirror row_mask:0xf bank_mask:0xf bound_ctrl:1
	v_mov_b32_e32 v83, v82
	s_waitcnt lgkmcnt(0)
	s_nop 1
	v_permlane16_swap_b32_e32 v82, v83
	v_add_f32_e32 v82, v82, v83
	v_mov_b32_e32 v83, v82
	s_waitcnt lgkmcnt(0)
	s_nop 1
	v_permlane32_swap_b32_e32 v82, v83
	v_add_f32_e32 v82, v82, v83
	v_fmamk_f32 v82, v82, 0x3c000000, v241
	v_cmp_gt_f32_e32 vcc, s68, v82
	v_mul_f32_e32 v83, 0x4b800000, v82
	s_nop 0
	v_cndmask_b32_e32 v82, v82, v83, vcc
	v_rsq_f32_e32 v82, v82
	s_nop 0
	v_mul_f32_e32 v83, 0x45800000, v82
	v_cndmask_b32_e32 v82, v82, v83, vcc
	v_mul_f32_e32 v77, v82, v77
	v_mul_f32_e32 v76, v82, v76
	v_mul_f32_e32 v77, v101, v77
	v_mul_f32_e32 v76, v100, v76
	v_mul_f32_e32 v82, v121, v77
	v_fma_f32 v82, v120, v76, -v82
	v_mul_f32_e32 v77, v120, v77
	v_cvt_pk_bf16_f32 v82, v82, v193
	global_store_short v[78:79], v82, off offset:256
	v_fmac_f32_e32 v77, v121, v76
	v_cvt_pk_bf16_f32 v76, v77, v193
	global_store_short v[78:79], v76, off offset:384
	v_lshl_add_u64 v[76:77], v[22:23], 0, v[80:81]
	global_store_dwordx2 v[76:77], v[72:73], off
	v_and_b32_e32 v73, 0xffff0000, v16
	v_and_b32_e32 v77, 0xffff0000, v17
	v_lshlrev_b32_e32 v72, 16, v16
	v_lshlrev_b32_e32 v76, 16, v17
	v_and_b32_e32 v17, 0xffff0000, v18
	v_and_b32_e32 v79, 0xffff0000, v19
	v_mov_b32_e32 v80, v73
	v_mov_b32_e32 v81, v77
	v_lshlrev_b32_e32 v16, 16, v18
	v_lshlrev_b32_e32 v78, 16, v19
	v_mov_b32_e32 v18, v72
	v_mov_b32_e32 v19, v76
	v_pk_mul_f32 v[80:81], v[80:81], v[80:81]
	v_mov_b32_e32 v82, v79
	v_mov_b32_e32 v83, v17
	v_pk_fma_f32 v[18:19], v[18:19], v[18:19], v[80:81]
	v_mov_b32_e32 v80, v78
	v_mov_b32_e32 v81, v16
	v_pk_mul_f32 v[82:83], v[82:83], v[82:83]
	v_add_f32_e32 v18, v18, v19
	v_pk_fma_f32 v[80:81], v[80:81], v[80:81], v[82:83]
	s_nop 0
	v_add_f32_e32 v18, v81, v18
	v_add_f32_e32 v18, v80, v18
	s_waitcnt lgkmcnt(0)
; __device__ __forceinline__ unsigned cvt_pk_bf16(float lo, float hi) { unsigned r; asm volatile("v_cvt_pk_bf16_f32 %0, %1, %2" : "=v"(r) : "v"(lo), "v"(hi)); return r; }
; __device__ __forceinline__ float bf2f(unsigned short x) { return __uint_as_float(((unsigned)x) << 16); }
; __device__ __forceinline__ void prep_phase(const PrepArgs& a, const int wv) {
;     ...
;         { const bf16x8 q8 = cur.bq;
;           const f32x4 v0 = {bf2f((unsigned short)q8[0]), bf2f((unsigned short)q8[1]), bf2f((unsigned short)q8[2]), bf2f((unsigned short)q8[3])}, v1 = {bf2f((unsigned short)q8[4]), bf2f((unsigned short)q8[5]), bf2f((unsigned short)q8[6]), bf2f((unsigned short)q8[7])};
;           const float ss = (v0[0] * v0[0] + v0[1] * v0[1]) + (v0[2] * v0[2] + v0[3] * v0[3]) + (v1[0] * v1[0] + v1[1] * v1[1]) + (v1[2] * v1[2] + v1[3] * v1[3]);
;           const float rinv = rsqrtf(wave_sum(ss, lane) * (1.f / 512.f) + EPS); const f32x4 o0 = v0 * rinv * gb0, o1 = v1 * rinv * gb1;
;           u32x4 w; w.x = cvt_pk_bf16(o0[0], o0[1]); w.y = cvt_pk_bf16(o0[2], o0[3]); w.z = cvt_pk_bf16(o1[0], o1[1]); w.w = cvt_pk_bf16(o1[2], o1[3]);
;           *(u32x4*)(a.BQN + (size_t)row * 512 + lane * 8) = w; }
;         { const u32x2 k4 = cur.bkv; const f32x4 v = {__uint_as_float(k4.x << 16), __uint_as_float(k4.x & 0xffff0000u), __uint_as_float(k4.y << 16), __uint_as_float(k4.y & 0xffff0000u)};
;           const float rinv = rsqrtf(wave_sum((v[0] * v[0] + v[1] * v[1]) + (v[2] * v[2] + v[3] * v[3]), lane) * (1.f / 256.f) + EPS);
;           const f32x4 o = v * rinv * gkv; u32x2 w; w.x = cvt_pk_bf16(o[0], o[1]); w.y = cvt_pk_bf16(o[2], o[3]);
;           *(u32x2*)(a.BKVN + (size_t)row * 256 + lane * 4) = w; }
;         if (lane < 32) { const float x1 = bf2f((unsigned short)cur.r1), x2 = bf2f((unsigned short)cur.r2); const unsigned w = cvt_pk_bf16(x1 * cB - x2 * sB, x1 * sB + x2 * cB);
; #pragma unroll
;             for (int h = 0; h < 4; ++h) *(unsigned*)(a.KB + kvrow * 768 + h * 192 + 128 + 2 * lane) = w; }
	s_nop 1
	v_add_f32_dpp v18, v18, v18 quad_perm:[1,0,3,2] row_mask:0xf bank_mask:0xf bound_ctrl:1
	s_waitcnt lgkmcnt(0)
	s_nop 1
	v_add_f32_dpp v18, v18, v18 quad_perm:[2,3,0,1] row_mask:0xf bank_mask:0xf bound_ctrl:1
	s_waitcnt lgkmcnt(0)
	s_nop 1
	v_add_f32_dpp v18, v18, v18 row_half_mirror row_mask:0xf bank_mask:0xf bound_ctrl:1
	s_waitcnt lgkmcnt(0)
	s_nop 1
	v_add_f32_dpp v18, v18, v18 row_mirror row_mask:0xf bank_mask:0xf bound_ctrl:1
	v_mov_b32_e32 v19, v18
	s_waitcnt lgkmcnt(0)
	s_nop 1
	v_permlane16_swap_b32_e32 v18, v19
	v_add_f32_e32 v18, v18, v19
	v_mov_b32_e32 v19, v18
	s_waitcnt lgkmcnt(0)
	s_nop 1
	v_permlane32_swap_b32_e32 v18, v19
	v_add_f32_e32 v18, v18, v19
	v_fmamk_f32 v18, v18, 0x3b000000, v241
	v_cmp_gt_f32_e32 vcc, s68, v18
	v_mul_f32_e32 v19, 0x4b800000, v18
	s_nop 0
	v_cndmask_b32_e32 v18, v18, v19, vcc
	v_rsq_f32_e32 v18, v18
	s_nop 0
	v_mul_f32_e32 v19, 0x45800000, v18
	v_cndmask_b32_e32 v18, v18, v19, vcc
	v_pk_mul_f32 v[72:73], v[18:19], v[72:73] op_sel_hi:[0,1]
	v_pk_mul_f32 v[76:77], v[18:19], v[76:77] op_sel_hi:[0,1]
	v_pk_mul_f32 v[16:17], v[18:19], v[16:17] op_sel_hi:[0,1]
	v_pk_mul_f32 v[18:19], v[18:19], v[78:79] op_sel_hi:[0,1]
	v_pk_mul_f32 v[72:73], v[4:5], v[72:73]
	v_pk_mul_f32 v[78:79], v[2:3], v[18:19]
	v_pk_mul_f32 v[18:19], v[0:1], v[16:17]
	v_pk_mul_f32 v[76:77], v[6:7], v[76:77]
	v_cvt_pk_bf16_f32 v16, v72, v73
	v_lshl_add_u64 v[72:73], s[16:17], 0, v[34:35]
	v_cvt_pk_bf16_f32 v17, v76, v77
	v_cvt_pk_bf16_f32 v18, v18, v19
	v_cvt_pk_bf16_f32 v19, v78, v79
	global_store_dwordx4 v[72:73], v[16:19], off
	s_nop 1
	v_and_b32_e32 v19, 0xffff0000, v21
	v_and_b32_e32 v18, 0xffff0000, v20
	v_lshlrev_b32_e32 v17, 16, v21
	v_lshlrev_b32_e32 v16, 16, v20
	v_pk_mul_f32 v[20:21], v[18:19], v[18:19]
	v_mov_b32_e32 v72, v16
	v_pk_fma_f32 v[20:21], v[16:17], v[16:17], v[20:21]
	v_mov_b32_e32 v73, v18
	v_add_f32_e32 v20, v20, v21
	v_mov_b32_e32 v18, v17
	s_waitcnt lgkmcnt(0)
	s_nop 1
	v_add_f32_dpp v20, v20, v20 quad_perm:[1,0,3,2] row_mask:0xf bank_mask:0xf bound_ctrl:1
	s_waitcnt lgkmcnt(0)
	s_nop 1
	v_add_f32_dpp v20, v20, v20 quad_perm:[2,3,0,1] row_mask:0xf bank_mask:0xf bound_ctrl:1
	s_waitcnt lgkmcnt(0)
	s_nop 1
	v_add_f32_dpp v20, v20, v20 row_half_mirror row_mask:0xf bank_mask:0xf bound_ctrl:1
	s_waitcnt lgkmcnt(0)
	s_nop 1
	v_add_f32_dpp v20, v20, v20 row_mirror row_mask:0xf bank_mask:0xf bound_ctrl:1
	v_mov_b32_e32 v21, v20
	s_waitcnt lgkmcnt(0)
	s_nop 1
	v_permlane16_swap_b32_e32 v20, v21
	v_add_f32_e32 v20, v20, v21
	v_mov_b32_e32 v21, v20
	s_waitcnt lgkmcnt(0)
	s_nop 1
	v_permlane32_swap_b32_e32 v20, v21
	v_add_f32_e32 v20, v20, v21
	v_fmamk_f32 v20, v20, 0x3b800000, v241
	v_cmp_gt_f32_e32 vcc, s68, v20
	v_mul_f32_e32 v21, 0x4b800000, v20
	s_nop 0
	v_cndmask_b32_e32 v20, v20, v21, vcc
	v_rsq_f32_e32 v20, v20
	s_nop 0
	v_mul_f32_e32 v21, 0x45800000, v20
	v_cndmask_b32_e32 v20, v20, v21, vcc
	v_pk_mul_f32 v[72:73], v[20:21], v[72:73] op_sel_hi:[0,1]
	v_pk_mul_f32 v[16:17], v[20:21], v[18:19] op_sel_hi:[0,1]
	v_pk_mul_f32 v[16:17], v[10:11], v[16:17]
	v_pk_mul_f32 v[18:19], v[8:9], v[72:73]
	s_nop 0
	v_cvt_pk_bf16_f32 v18, v18, v19
	v_cvt_pk_bf16_f32 v19, v16, v17
	v_lshl_add_u64 v[16:17], s[16:17], 0, v[32:33]
	global_store_dwordx2 v[16:17], v[18:19], off
	s_and_saveexec_b64 s[44:45], s[6:7]
	s_cbranch_execz .LBB0_679
	v_lshlrev_b32_e32 v17, 16, v113
	v_lshlrev_b32_e32 v16, 16, v112
	v_mul_f32_e32 v18, v103, v17
	v_fma_f32 v18, v102, v16, -v18
	v_mul_f32_e32 v16, v103, v16
	v_fmac_f32_e32 v16, v102, v17
	v_cvt_pk_bf16_f32 v20, v18, v16
	v_mad_u64_u32 v[16:17], s[4:5], v74, s73, v[26:27]
	v_mov_b32_e32 v18, v17
	v_mad_u64_u32 v[18:19], s[4:5], v75, s73, v[18:19]
	v_mov_b32_e32 v17, v18
	global_store_dword v[16:17], v20, off offset:256
	global_store_dword v[16:17], v20, off offset:640
	global_store_dword v[16:17], v20, off offset:1024
	global_store_dword v[16:17], v20, off offset:1408
	s_branch .LBB0_679
